# NSA lean iteration: tile-A K fragment ds_reads issued at the top of the iteration head (before the selection-mask computation)
# baseline (speedup 1.0000x reference)
.LBB0_1463:
	s_cmp_eq_u32 s63, 2
	s_cbranch_scc0 .Lm2_no
	s_add_i32 s98, s54, 1
	s_cmp_ge_i32 s98, s53
	s_cbranch_scc1 .Lm2_no
	v_cmp_eq_f32_e64 s[18:19], s73, v222
	s_cmp_lg_u64 s[18:19], 0
	s_cbranch_scc1 .Lm2_no
	s_add_i32 s21, s38, s45
	s_and_b32 s20, s45, 2
	s_add_i32 s54, s54, 1
	s_mov_b64 s[94:95], 0
	s_lshl_b32 s30, s20, 13
	v_add_u32_e32 v8, s30, v169
	ds_read_b128 v[10:13], v8
	ds_read_b128 v[14:17], v8 offset:512
	ds_read_b128 v[174:177], v8 offset:2048
	ds_read_b128 v[178:181], v8 offset:2560
	ds_read_b128 v[182:185], v8 offset:4096
	ds_read_b128 v[186:189], v8 offset:4608
	ds_read_b128 v[228:231], v8 offset:6144
	ds_read_b128 v[232:235], v8 offset:6656
	v_add_u32_e32 v3, s30, v193
	s_lshr_b32 s0, s21, 5
	s_cmp_lt_u32 s0, 2
	s_cselect_b64 s[98:99], -1, 0
	s_bitcmp1_b32 s0, 0
	s_cselect_b64 s[0:1], -1, 0
	s_and_b32 s28, s21, 31
	v_cndmask_b32_e64 v5, v130, v131, s[0:1]
	v_cndmask_b32_e64 v6, v132, v133, s[0:1]
	v_cndmask_b32_e64 v5, v6, v5, s[98:99]
	v_lshrrev_b32_e32 v5, s28, v5
	v_and_b32_e32 v6, 1, v5
	v_bfe_u32 v9, v5, 1, 1
	v_xor_b32_e32 v7, 0x80000000, v222
	v_cmp_eq_u32_e32 vcc, 1, v6
	v_cmp_eq_u32_e64 s[98:99], 1, v9
	v_add_f32_e32 v4, v7, v201
	s_cmp_lg_u64 vcc, 0
	s_cselect_b32 s55, 1, 0
	v_cndmask_b32_e32 v82, v4, v7, vcc
	v_cndmask_b32_e64 v50, v4, v7, s[98:99]
	s_cmp_lg_u64 s[98:99], 0
	s_cselect_b32 s0, 2, 0
	s_or_b32 s55, s55, s0
	s_cmp_eq_u32 s55, 3
	s_cbranch_scc0 .Lm2_partial
	v_mov_b32_e32 v83, v82
	v_mov_b64_e32 v[84:85], v[82:83]
	v_mov_b64_e32 v[86:87], v[82:83]
	v_mov_b64_e32 v[88:89], v[82:83]
	v_mov_b64_e32 v[90:91], v[82:83]
	v_mov_b64_e32 v[92:93], v[82:83]
	v_mov_b64_e32 v[94:95], v[82:83]
	v_mov_b64_e32 v[96:97], v[82:83]
	v_mov_b32_e32 v51, v50
	v_mov_b64_e32 v[52:53], v[50:51]
	s_waitcnt lgkmcnt(7)
	v_mfma_f32_32x32x16_bf16 v[98:113], v[10:13], v[114:117], v[82:97]
	ds_read_b128 v[10:13], v8 offset:8192
	v_mov_b64_e32 v[54:55], v[50:51]
	v_mov_b64_e32 v[56:57], v[50:51]
	v_mov_b64_e32 v[58:59], v[50:51]
	v_mov_b64_e32 v[60:61], v[50:51]
	v_mov_b64_e32 v[62:63], v[50:51]
	s_waitcnt lgkmcnt(7)
	v_mfma_f32_32x32x16_bf16 v[82:97], v[14:17], v[114:117], v[82:97]
	ds_read_b128 v[14:17], v8 offset:8704
	v_mov_b64_e32 v[64:65], v[50:51]
	s_add_i32 s0, s21, 2
	s_ashr_i32 s1, s0, 31
	s_lshl_b64 s[0:1], s[0:1], 6
	s_add_u32 s0, s0, s84
	s_waitcnt lgkmcnt(7)
	v_mfma_f32_32x32x16_bf16 v[98:113], v[174:177], v[118:121], v[98:113]
	ds_read_b128 v[174:177], v8 offset:10240
	s_addc_u32 s1, s1, s85
	s_lshl_b64 s[0:1], s[0:1], 7
	s_add_u32 s28, s86, s0
	s_addc_u32 s29, s87, s1
	s_sub_i32 s31, s37, s30
	s_waitcnt lgkmcnt(7)
	v_mfma_f32_32x32x16_bf16 v[82:97], v[178:181], v[118:121], v[82:97]
	ds_read_b128 v[178:181], v8 offset:10752
	s_add_i32 s31, s31, 0x4000
	v_lshlrev_b32_e32 v5, 7, v138
	s_mov_b32 m0, s31
	s_movk_i32 s30, 0x80
	global_load_lds_dwordx4 v5, s[28:29]
	s_waitcnt lgkmcnt(7)
	v_mfma_f32_32x32x16_bf16 v[98:113], v[182:185], v[122:125], v[98:113]
	ds_read_b128 v[182:185], v8 offset:12288
	v_mad_u64_u32 v[226:227], vcc, v168, s30, v[134:135]
	s_add_i32 s31, s31, 0x8000
	v_lshl_add_u64 v[6:7], v[226:227], 0, s[0:1]
	s_mov_b32 m0, s31
	s_cmp_lt_i32 s45, s44
	s_waitcnt lgkmcnt(7)
	v_mfma_f32_32x32x16_bf16 v[82:97], v[186:189], v[122:125], v[82:97]
	ds_read_b128 v[186:189], v8 offset:12800
	global_load_lds_dwordx4 v[6:7], off
	s_cselect_b32 s98, 0x2000, 0
	s_add_u32 s28, s28, s98
	s_waitcnt lgkmcnt(7)
	v_mfma_f32_32x32x16_bf16 v[98:113], v[228:231], v[126:129], v[98:113]
	ds_read_b128 v[228:231], v8 offset:14336
	s_addc_u32 s29, s29, 0
	s_add_u32 s0, s0, s98
	s_addc_u32 s1, s1, 0
	s_sub_i32 s31, s31, 0x6000
	s_mov_b32 m0, s31
	s_waitcnt lgkmcnt(7)
	v_mfma_f32_32x32x16_bf16 v[82:97], v[232:235], v[126:129], v[82:97]
	ds_read_b128 v[232:235], v8 offset:14848
	v_lshl_add_u64 v[6:7], v[226:227], 0, s[0:1]
	global_load_lds_dwordx4 v5, s[28:29]
	s_add_i32 s31, s31, 0x8000
	s_waitcnt lgkmcnt(7)
	v_mfma_f32_32x32x16_bf16 v[66:81], v[10:13], v[114:117], v[50:65]
	ds_read_b64_tr_b16 v[10:11], v3 offset:32768
	ds_read_b64_tr_b16 v[12:13], v3 offset:33280
	s_mov_b32 m0, s31
	s_nop 0
	global_load_lds_dwordx4 v[6:7], off
	s_waitcnt lgkmcnt(8)
	v_mfma_f32_32x32x16_bf16 v[50:65], v[14:17], v[114:117], v[50:65]
	ds_read_b64_tr_b16 v[14:15], v3 offset:36864
	ds_read_b64_tr_b16 v[16:17], v3 offset:37376
	v_exp_f32_e32 v98, v98
	v_exp_f32_e32 v99, v99
	v_exp_f32_e32 v100, v100
	s_waitcnt lgkmcnt(9)
	v_mfma_f32_32x32x16_bf16 v[66:81], v[174:177], v[118:121], v[66:81]
	ds_read_b64_tr_b16 v[174:175], v3 offset:33792
	ds_read_b64_tr_b16 v[176:177], v3 offset:34304
	v_exp_f32_e32 v101, v101
	v_exp_f32_e32 v102, v102
	v_exp_f32_e32 v103, v103
	s_waitcnt lgkmcnt(10)
	v_mfma_f32_32x32x16_bf16 v[50:65], v[178:181], v[118:121], v[50:65]
	ds_read_b64_tr_b16 v[178:179], v3 offset:37888
	ds_read_b64_tr_b16 v[180:181], v3 offset:38400
	v_exp_f32_e32 v104, v104
	v_exp_f32_e32 v105, v105
	v_cvt_pk_bf16_f32 v236, v98, v99
	s_waitcnt lgkmcnt(11)
	v_mfma_f32_32x32x16_bf16 v[66:81], v[182:185], v[122:125], v[66:81]
	ds_read_b64_tr_b16 v[182:183], v3 offset:34816
	ds_read_b64_tr_b16 v[184:185], v3 offset:35328
	v_cvt_pk_bf16_f32 v237, v100, v101
	v_cvt_pk_bf16_f32 v238, v102, v103
	v_cvt_pk_bf16_f32 v239, v104, v105
	v_exp_f32_e32 v106, v106
	s_waitcnt lgkmcnt(12)
	v_mfma_f32_32x32x16_bf16 v[50:65], v[186:189], v[122:125], v[50:65]
	ds_read_b64_tr_b16 v[186:187], v3 offset:38912
	ds_read_b64_tr_b16 v[188:189], v3 offset:39424
	v_exp_f32_e32 v107, v107
	v_exp_f32_e32 v108, v108
	v_exp_f32_e32 v109, v109
	s_waitcnt lgkmcnt(13)
	v_mfma_f32_32x32x16_bf16 v[66:81], v[228:231], v[126:129], v[66:81]
	ds_read_b64_tr_b16 v[228:229], v3 offset:35840
	ds_read_b64_tr_b16 v[230:231], v3 offset:36352
	v_exp_f32_e32 v110, v110
	v_exp_f32_e32 v111, v111
	v_exp_f32_e32 v112, v112
	s_waitcnt lgkmcnt(14)
	v_mfma_f32_32x32x16_bf16 v[50:65], v[232:235], v[126:129], v[50:65]
	s_waitcnt lgkmcnt(13)
	ds_read_b64_tr_b16 v[232:233], v3 offset:39936
	ds_read_b64_tr_b16 v[234:235], v3 offset:40448
	v_exp_f32_e32 v113, v113
	v_cvt_pk_bf16_f32 v240, v106, v107
	v_cvt_pk_bf16_f32 v241, v108, v109
	v_cvt_pk_bf16_f32 v242, v110, v111
	s_waitcnt lgkmcnt(14)
	v_mfma_f32_32x32x16_bf16 v[34:49], v[236:239], v[10:13], v[34:49]
	s_waitcnt lgkmcnt(13)
	ds_read_b64_tr_b16 v[10:11], v3 offset:40960
	ds_read_b64_tr_b16 v[12:13], v3 offset:41472
	v_cvt_pk_bf16_f32 v243, v112, v113
	v_exp_f32_e32 v82, v82
	v_exp_f32_e32 v83, v83
	s_waitcnt lgkmcnt(14)
	v_mfma_f32_32x32x16_bf16 v[18:33], v[236:239], v[14:17], v[18:33]
	s_waitcnt lgkmcnt(13)
	ds_read_b64_tr_b16 v[14:15], v3 offset:45056
	ds_read_b64_tr_b16 v[16:17], v3 offset:45568
	v_exp_f32_e32 v84, v84
	v_exp_f32_e32 v85, v85
	v_exp_f32_e32 v86, v86
	s_waitcnt lgkmcnt(14)
	v_mfma_f32_32x32x16_bf16 v[34:49], v[240:243], v[174:177], v[34:49]
	s_waitcnt lgkmcnt(13)
	ds_read_b64_tr_b16 v[174:175], v3 offset:41984
	ds_read_b64_tr_b16 v[176:177], v3 offset:42496
	v_exp_f32_e32 v87, v87
	v_exp_f32_e32 v88, v88
	v_exp_f32_e32 v89, v89
	s_waitcnt lgkmcnt(14)
	v_mfma_f32_32x32x16_bf16 v[18:33], v[240:243], v[178:181], v[18:33]
	s_waitcnt lgkmcnt(13)
	ds_read_b64_tr_b16 v[178:179], v3 offset:46080
	ds_read_b64_tr_b16 v[180:181], v3 offset:46592
	v_cvt_pk_bf16_f32 v244, v82, v83
	v_cvt_pk_bf16_f32 v245, v84, v85
	v_cvt_pk_bf16_f32 v246, v86, v87
	v_cvt_pk_bf16_f32 v247, v88, v89
	v_exp_f32_e32 v90, v90
	v_exp_f32_e32 v91, v91
	s_waitcnt lgkmcnt(14)
	v_mfma_f32_32x32x16_bf16 v[34:49], v[244:247], v[182:185], v[34:49]
	s_waitcnt lgkmcnt(13)
	ds_read_b64_tr_b16 v[182:183], v3 offset:43008
	ds_read_b64_tr_b16 v[184:185], v3 offset:43520
	v_exp_f32_e32 v92, v92
	v_exp_f32_e32 v93, v93
	v_exp_f32_e32 v94, v94
	s_waitcnt lgkmcnt(14)
	v_mfma_f32_32x32x16_bf16 v[18:33], v[244:247], v[186:189], v[18:33]
	s_waitcnt lgkmcnt(13)
	ds_read_b64_tr_b16 v[186:187], v3 offset:47104
	ds_read_b64_tr_b16 v[188:189], v3 offset:47616
	v_exp_f32_e32 v95, v95
	v_exp_f32_e32 v96, v96
	v_exp_f32_e32 v97, v97
	v_cvt_pk_bf16_f32 v248, v90, v91
	v_cvt_pk_bf16_f32 v249, v92, v93
	v_cvt_pk_bf16_f32 v250, v94, v95
	v_cvt_pk_bf16_f32 v251, v96, v97
	v_exp_f32_e32 v66, v66
	v_exp_f32_e32 v67, v67
	s_waitcnt lgkmcnt(14)
	v_mfma_f32_32x32x16_bf16 v[34:49], v[248:251], v[228:231], v[34:49]
	s_waitcnt lgkmcnt(13)
	ds_read_b64_tr_b16 v[228:229], v3 offset:44032
	ds_read_b64_tr_b16 v[230:231], v3 offset:44544
	v_exp_f32_e32 v68, v68
	v_exp_f32_e32 v69, v69
	v_exp_f32_e32 v70, v70
	s_waitcnt lgkmcnt(14)
	v_mfma_f32_32x32x16_bf16 v[18:33], v[248:251], v[232:235], v[18:33]
	s_waitcnt lgkmcnt(13)
	ds_read_b64_tr_b16 v[232:233], v3 offset:48128
	ds_read_b64_tr_b16 v[234:235], v3 offset:48640
	v_exp_f32_e32 v71, v71
	v_exp_f32_e32 v72, v72
	v_exp_f32_e32 v73, v73
	v_cvt_pk_bf16_f32 v236, v66, v67
	v_cvt_pk_bf16_f32 v237, v68, v69
	v_cvt_pk_bf16_f32 v238, v70, v71
	v_cvt_pk_bf16_f32 v239, v72, v73
	v_exp_f32_e32 v74, v74
	v_exp_f32_e32 v75, v75
	s_waitcnt lgkmcnt(14)
	v_mfma_f32_32x32x16_bf16 v[34:49], v[236:239], v[10:13], v[34:49]
	v_exp_f32_e32 v76, v76
	v_exp_f32_e32 v77, v77
	v_exp_f32_e32 v78, v78
	s_waitcnt lgkmcnt(12)
	v_mfma_f32_32x32x16_bf16 v[18:33], v[236:239], v[14:17], v[18:33]
	v_exp_f32_e32 v79, v79
	v_exp_f32_e32 v80, v80
	v_exp_f32_e32 v81, v81
	v_cvt_pk_bf16_f32 v240, v74, v75
	v_cvt_pk_bf16_f32 v241, v76, v77
	v_cvt_pk_bf16_f32 v242, v78, v79
	v_cvt_pk_bf16_f32 v243, v80, v81
	v_exp_f32_e32 v50, v50
	v_exp_f32_e32 v51, v51
	s_waitcnt lgkmcnt(10)
	v_mfma_f32_32x32x16_bf16 v[34:49], v[240:243], v[174:177], v[34:49]
	v_exp_f32_e32 v52, v52
	v_exp_f32_e32 v53, v53
	v_exp_f32_e32 v54, v54
	s_waitcnt lgkmcnt(8)
	v_mfma_f32_32x32x16_bf16 v[18:33], v[240:243], v[178:181], v[18:33]
	v_exp_f32_e32 v55, v55
	v_exp_f32_e32 v56, v56
	v_exp_f32_e32 v57, v57
	v_cvt_pk_bf16_f32 v244, v50, v51
	v_cvt_pk_bf16_f32 v245, v52, v53
	v_cvt_pk_bf16_f32 v246, v54, v55
	v_cvt_pk_bf16_f32 v247, v56, v57
	v_exp_f32_e32 v58, v58
	v_exp_f32_e32 v59, v59
	s_waitcnt lgkmcnt(6)
	v_mfma_f32_32x32x16_bf16 v[34:49], v[244:247], v[182:185], v[34:49]
	v_exp_f32_e32 v60, v60
	v_exp_f32_e32 v61, v61
	v_exp_f32_e32 v62, v62
	s_waitcnt lgkmcnt(4)
	v_mfma_f32_32x32x16_bf16 v[18:33], v[244:247], v[186:189], v[18:33]
	v_exp_f32_e32 v63, v63
	v_exp_f32_e32 v64, v64
	v_exp_f32_e32 v65, v65
	v_cvt_pk_bf16_f32 v248, v58, v59
	v_cvt_pk_bf16_f32 v249, v60, v61
	v_cvt_pk_bf16_f32 v250, v62, v63
	v_cvt_pk_bf16_f32 v251, v64, v65
	v_pk_add_f32 v[4:5], v[98:99], v[100:101]
	v_pk_add_f32 v[6:7], v[82:83], v[84:85]
	s_waitcnt lgkmcnt(2)
	v_mfma_f32_32x32x16_bf16 v[34:49], v[248:251], v[228:231], v[34:49]
	v_pk_add_f32 v[4:5], v[4:5], v[102:103]
	v_pk_add_f32 v[6:7], v[6:7], v[86:87]
	v_pk_add_f32 v[4:5], v[4:5], v[104:105]
	v_pk_add_f32 v[6:7], v[6:7], v[88:89]
	v_pk_add_f32 v[4:5], v[4:5], v[106:107]
	s_waitcnt lgkmcnt(0)
	v_mfma_f32_32x32x16_bf16 v[18:33], v[248:251], v[232:235], v[18:33]
	v_pk_add_f32 v[6:7], v[6:7], v[90:91]
	v_pk_add_f32 v[4:5], v[4:5], v[108:109]
	v_pk_add_f32 v[6:7], v[6:7], v[92:93]
	v_pk_add_f32 v[4:5], v[4:5], v[110:111]
	v_pk_add_f32 v[6:7], v[6:7], v[94:95]
	v_pk_add_f32 v[4:5], v[4:5], v[112:113]
	v_pk_add_f32 v[6:7], v[6:7], v[96:97]
	v_add_f32_e32 v6, v6, v7
	v_add_f32_e32 v4, v4, v5
	v_add_f32_e32 v4, v6, v4
	v_mov_b32_e32 v5, v4
	v_add_f32_e32 v225, v225, v4
	v_pk_add_f32 v[4:5], v[66:67], v[68:69]
	v_pk_add_f32 v[6:7], v[50:51], v[52:53]
	v_pk_add_f32 v[4:5], v[4:5], v[70:71]
	v_pk_add_f32 v[6:7], v[6:7], v[54:55]
	v_pk_add_f32 v[4:5], v[4:5], v[72:73]
	v_pk_add_f32 v[6:7], v[6:7], v[56:57]
	v_pk_add_f32 v[4:5], v[4:5], v[74:75]
	v_pk_add_f32 v[6:7], v[6:7], v[58:59]
	v_pk_add_f32 v[4:5], v[4:5], v[76:77]
	v_pk_add_f32 v[6:7], v[6:7], v[60:61]
	v_pk_add_f32 v[4:5], v[4:5], v[78:79]
	v_pk_add_f32 v[6:7], v[6:7], v[62:63]
	v_pk_add_f32 v[4:5], v[4:5], v[80:81]
	v_pk_add_f32 v[6:7], v[6:7], v[64:65]
	v_add_f32_e32 v6, v6, v7
	v_add_f32_e32 v4, v4, v5
	v_add_f32_e32 v4, v6, v4
	v_add_f32_e32 v225, v225, v4
	s_mov_b64 s[20:21], 0
	s_mov_b32 s30, 0x437f0000
	v_cmp_nge_f32_e32 vcc, s30, v5
	v_cmp_nge_f32_e64 s[98:99], s30, v4
	s_or_b64 s[98:99], vcc, s[98:99]
	s_cbranch_scc1 .Lm2_rare_full
	s_waitcnt vmcnt(0) lgkmcnt(0)
	s_barrier
	s_add_i32 s45, s45, 2
	s_branch .LBB0_1463

.Lm2_partial:
	s_cmp_eq_u32 s55, 0
	s_cbranch_scc1 .Lm2_none
	s_cmp_eq_u32 s55, 2
	s_cbranch_scc0 .Lm2_st
	v_add_u32_e32 v8, 0x2000, v8
	v_add_u32_e32 v3, 0x2000, v3
	v_mov_b32_e32 v82, v50
	s_waitcnt lgkmcnt(0)
	ds_read_b128 v[10:13], v8
	ds_read_b128 v[14:17], v8 offset:512
	ds_read_b128 v[174:177], v8 offset:2048
	ds_read_b128 v[178:181], v8 offset:2560
	ds_read_b128 v[182:185], v8 offset:4096
	ds_read_b128 v[186:189], v8 offset:4608
	ds_read_b128 v[228:231], v8 offset:6144
	ds_read_b128 v[232:235], v8 offset:6656
.Lm2_st:
	v_mov_b32_e32 v83, v82
	v_mov_b64_e32 v[84:85], v[82:83]
	v_mov_b64_e32 v[86:87], v[82:83]
	v_mov_b64_e32 v[88:89], v[82:83]
	v_mov_b64_e32 v[90:91], v[82:83]
	v_mov_b64_e32 v[92:93], v[82:83]
	v_mov_b64_e32 v[94:95], v[82:83]
	v_mov_b64_e32 v[96:97], v[82:83]
	s_add_i32 s0, s21, 2
	s_ashr_i32 s1, s0, 31
	s_waitcnt lgkmcnt(7)
	v_mfma_f32_32x32x16_bf16 v[98:113], v[10:13], v[114:117], v[82:97]
	ds_read_b64_tr_b16 v[10:11], v3 offset:32768
	ds_read_b64_tr_b16 v[12:13], v3 offset:33280
	s_lshl_b64 s[0:1], s[0:1], 6
	s_add_u32 s0, s0, s84
	s_addc_u32 s1, s1, s85
	s_lshl_b64 s[0:1], s[0:1], 7
	s_add_u32 s28, s86, s0
	s_waitcnt lgkmcnt(8)
	v_mfma_f32_32x32x16_bf16 v[82:97], v[14:17], v[114:117], v[82:97]
	ds_read_b64_tr_b16 v[14:15], v3 offset:36864
	ds_read_b64_tr_b16 v[16:17], v3 offset:37376
	s_addc_u32 s29, s87, s1
	s_sub_i32 s31, s37, s30
	s_add_i32 s31, s31, 0x4000
	v_lshlrev_b32_e32 v5, 7, v138
	s_mov_b32 m0, s31
	s_waitcnt lgkmcnt(9)
	v_mfma_f32_32x32x16_bf16 v[98:113], v[174:177], v[118:121], v[98:113]
	ds_read_b64_tr_b16 v[174:175], v3 offset:33792
	ds_read_b64_tr_b16 v[176:177], v3 offset:34304
	s_movk_i32 s30, 0x80
	global_load_lds_dwordx4 v5, s[28:29]
	v_mad_u64_u32 v[226:227], vcc, v168, s30, v[134:135]
	s_waitcnt lgkmcnt(10)
	v_mfma_f32_32x32x16_bf16 v[82:97], v[178:181], v[118:121], v[82:97]
	ds_read_b64_tr_b16 v[178:179], v3 offset:37888
	ds_read_b64_tr_b16 v[180:181], v3 offset:38400
	s_add_i32 s31, s31, 0x8000
	v_lshl_add_u64 v[6:7], v[226:227], 0, s[0:1]
	s_mov_b32 m0, s31
	s_cmp_lt_i32 s45, s44
	global_load_lds_dwordx4 v[6:7], off
	s_waitcnt lgkmcnt(11)
	v_mfma_f32_32x32x16_bf16 v[98:113], v[182:185], v[122:125], v[98:113]
	ds_read_b64_tr_b16 v[182:183], v3 offset:34816
	ds_read_b64_tr_b16 v[184:185], v3 offset:35328
	s_cselect_b32 s98, 0x2000, 0
	s_add_u32 s28, s28, s98
	s_addc_u32 s29, s29, 0
	s_add_u32 s0, s0, s98
	s_addc_u32 s1, s1, 0
	s_waitcnt lgkmcnt(12)
	v_mfma_f32_32x32x16_bf16 v[82:97], v[186:189], v[122:125], v[82:97]
	ds_read_b64_tr_b16 v[186:187], v3 offset:38912
	ds_read_b64_tr_b16 v[188:189], v3 offset:39424
	s_sub_i32 s31, s31, 0x6000
	s_mov_b32 m0, s31
	v_lshl_add_u64 v[6:7], v[226:227], 0, s[0:1]
	global_load_lds_dwordx4 v5, s[28:29]
	s_waitcnt lgkmcnt(13)
	v_mfma_f32_32x32x16_bf16 v[98:113], v[228:231], v[126:129], v[98:113]
	ds_read_b64_tr_b16 v[228:229], v3 offset:35840
	ds_read_b64_tr_b16 v[230:231], v3 offset:36352
	s_add_i32 s31, s31, 0x8000
	s_mov_b32 m0, s31
	s_nop 0
	global_load_lds_dwordx4 v[6:7], off
	s_waitcnt lgkmcnt(14)
	v_mfma_f32_32x32x16_bf16 v[82:97], v[232:235], v[126:129], v[82:97]
	s_waitcnt lgkmcnt(13)
	ds_read_b64_tr_b16 v[232:233], v3 offset:39936
	ds_read_b64_tr_b16 v[234:235], v3 offset:40448
	s_nop 0
	s_nop 0
	s_nop 0
	s_nop 0
	s_nop 0
	s_nop 0
	s_nop 0
	s_nop 0
	s_nop 0
	v_exp_f32_e32 v98, v98
	v_exp_f32_e32 v99, v99
	v_exp_f32_e32 v100, v100
	v_exp_f32_e32 v101, v101
	v_exp_f32_e32 v102, v102
	v_exp_f32_e32 v103, v103
	v_exp_f32_e32 v104, v104
	v_exp_f32_e32 v105, v105
	v_cvt_pk_bf16_f32 v236, v98, v99
	v_cvt_pk_bf16_f32 v237, v100, v101
	v_cvt_pk_bf16_f32 v238, v102, v103
	v_cvt_pk_bf16_f32 v239, v104, v105
	v_exp_f32_e32 v106, v106
	v_exp_f32_e32 v107, v107
	s_waitcnt lgkmcnt(14)
	v_mfma_f32_32x32x16_bf16 v[34:49], v[236:239], v[10:13], v[34:49]
	v_exp_f32_e32 v108, v108
	v_exp_f32_e32 v109, v109
	v_exp_f32_e32 v110, v110
	s_waitcnt lgkmcnt(12)
	v_mfma_f32_32x32x16_bf16 v[18:33], v[236:239], v[14:17], v[18:33]
	v_exp_f32_e32 v111, v111
	v_exp_f32_e32 v112, v112
	v_exp_f32_e32 v113, v113
	v_cvt_pk_bf16_f32 v240, v106, v107
	v_cvt_pk_bf16_f32 v241, v108, v109
	v_cvt_pk_bf16_f32 v242, v110, v111
	v_cvt_pk_bf16_f32 v243, v112, v113
	v_exp_f32_e32 v82, v82
	v_exp_f32_e32 v83, v83
	s_waitcnt lgkmcnt(10)
	v_mfma_f32_32x32x16_bf16 v[34:49], v[240:243], v[174:177], v[34:49]
	v_exp_f32_e32 v84, v84
	v_exp_f32_e32 v85, v85
	v_exp_f32_e32 v86, v86
	s_waitcnt lgkmcnt(8)
	v_mfma_f32_32x32x16_bf16 v[18:33], v[240:243], v[178:181], v[18:33]
	v_exp_f32_e32 v87, v87
	v_exp_f32_e32 v88, v88
	v_exp_f32_e32 v89, v89
	v_cvt_pk_bf16_f32 v244, v82, v83
	v_cvt_pk_bf16_f32 v245, v84, v85
	v_cvt_pk_bf16_f32 v246, v86, v87
	v_cvt_pk_bf16_f32 v247, v88, v89
	v_exp_f32_e32 v90, v90
	v_exp_f32_e32 v91, v91
	s_waitcnt lgkmcnt(6)
	v_mfma_f32_32x32x16_bf16 v[34:49], v[244:247], v[182:185], v[34:49]
	v_exp_f32_e32 v92, v92
	v_exp_f32_e32 v93, v93
	v_exp_f32_e32 v94, v94
	s_waitcnt lgkmcnt(4)
	v_mfma_f32_32x32x16_bf16 v[18:33], v[244:247], v[186:189], v[18:33]
	v_exp_f32_e32 v95, v95
	v_exp_f32_e32 v96, v96
	v_exp_f32_e32 v97, v97
	v_cvt_pk_bf16_f32 v248, v90, v91
	v_cvt_pk_bf16_f32 v249, v92, v93
	v_cvt_pk_bf16_f32 v250, v94, v95
	v_cvt_pk_bf16_f32 v251, v96, v97
	v_pk_add_f32 v[4:5], v[98:99], v[100:101]
	v_pk_add_f32 v[6:7], v[82:83], v[84:85]
	s_waitcnt lgkmcnt(2)
	v_mfma_f32_32x32x16_bf16 v[34:49], v[248:251], v[228:231], v[34:49]
	v_pk_add_f32 v[4:5], v[4:5], v[102:103]
	v_pk_add_f32 v[6:7], v[6:7], v[86:87]
	v_pk_add_f32 v[4:5], v[4:5], v[104:105]
	v_pk_add_f32 v[6:7], v[6:7], v[88:89]
	v_pk_add_f32 v[4:5], v[4:5], v[106:107]
	s_waitcnt lgkmcnt(0)
	v_mfma_f32_32x32x16_bf16 v[18:33], v[248:251], v[232:235], v[18:33]
	v_pk_add_f32 v[6:7], v[6:7], v[90:91]
	v_pk_add_f32 v[4:5], v[4:5], v[108:109]
	v_pk_add_f32 v[6:7], v[6:7], v[92:93]
	v_pk_add_f32 v[4:5], v[4:5], v[110:111]
	v_pk_add_f32 v[6:7], v[6:7], v[94:95]
	v_pk_add_f32 v[4:5], v[4:5], v[112:113]
	v_pk_add_f32 v[6:7], v[6:7], v[96:97]
	v_add_f32_e32 v6, v6, v7
	v_add_f32_e32 v4, v4, v5
	v_add_f32_e32 v4, v6, v4
	v_mov_b32_e32 v5, v4
	v_add_f32_e32 v225, v225, v4
	s_mov_b64 s[20:21], 0
	s_mov_b32 s30, 0x437f0000
	v_cmp_nge_f32_e32 vcc, s30, v5
	s_cmp_lg_u64 vcc, 0
	s_cbranch_scc1 .Lm2_rare_st
	s_waitcnt vmcnt(0) lgkmcnt(0)
	s_barrier
	s_add_i32 s45, s45, 2
	s_branch .LBB0_1463
